# P0b: next iteration's x rows touched during the current output stage so the next iteration's loads hit L2
# baseline (speedup 1.0000x reference)
.LBB0_138:
	v_lshl_add_u64 v[2:3], s[36:37], 0, v[204:205]
	v_lshl_add_u64 v[4:5], s[70:71], 0, v[204:205]
	v_lshl_add_u64 v[10:11], s[62:63], 0, v[204:205]
	v_lshl_add_u64 v[70:71], s[56:57], 0, v[204:205]
	global_load_dwordx4 v[6:9], v[74:75], off
	global_load_dwordx4 v[66:69], v[2:3], off
	global_load_dwordx4 v[58:61], v[2:3], off offset:1024
	global_load_dwordx4 v[54:57], v[2:3], off offset:3072
	global_load_dwordx4 v[62:65], v[2:3], off offset:2048
	global_load_dwordx4 v[50:53], v[4:5], off
	global_load_dwordx4 v[42:45], v[4:5], off offset:1024
	global_load_dwordx4 v[38:41], v[4:5], off offset:3072
	global_load_dwordx4 v[46:49], v[4:5], off offset:2048
	global_load_dwordx4 v[34:37], v[10:11], off
	global_load_dwordx4 v[30:33], v[10:11], off offset:1024
	global_load_dwordx4 v[26:29], v[10:11], off offset:2048
	global_load_dwordx4 v[22:25], v[10:11], off offset:3072
	global_load_dwordx4 v[18:21], v[70:71], off
	global_load_dwordx4 v[14:17], v[70:71], off offset:1024
	s_nop 0
	global_load_dwordx4 v[10:13], v[70:71], off offset:2048
	global_load_dwordx4 v[2:5], v[70:71], off offset:3072
	s_ashr_i32 s0, s38, 13
	v_lshl_add_u64 v[72:73], s[60:61], 0, v[200:201]
	v_lshl_add_u64 v[76:77], s[68:69], 0, v[200:201]
	s_mul_i32 s8, s0, 0x1800
	v_add_co_u32_e32 v82, vcc, s33, v72
	v_add_co_u32_e64 v80, s[0:1], s33, v76
	s_ashr_i32 s9, s8, 31
	v_addc_co_u32_e32 v83, vcc, 0, v73, vcc
	v_addc_co_u32_e64 v81, vcc, 0, v77, s[0:1]
	s_lshl_b64 s[0:1], s[8:9], 2
	s_add_u32 s78, s28, s0
	s_addc_u32 s79, s29, s1
	v_lshl_add_u64 v[96:97], s[30:31], 0, v[200:201]
	s_add_u32 s80, s78, 0x1000
	v_add_co_u32_e64 v76, s[6:7], s33, v96
	s_addc_u32 s81, s79, 0
	s_nop 0
	v_addc_co_u32_e64 v77, vcc, 0, v97, s[6:7]
	global_load_dwordx4 v[70:73], v92, s[78:79]
	global_load_dwordx4 v[96:99], v92, s[80:81]
	s_add_i32 s0, s38, 0x800
	s_ashr_i32 s0, s0, 13
	s_mulk_i32 s0, 0x1800
	s_ashr_i32 s1, s0, 31
	s_lshl_b64 s[0:1], s[0:1], 2
	s_add_u32 s54, s28, s0
	s_addc_u32 s55, s29, s1
	s_add_u32 s74, s54, 0x1000
	s_addc_u32 s75, s55, 0
	s_add_i32 s0, s38, 0x1000
	s_ashr_i32 s0, s0, 13
	s_mulk_i32 s0, 0x1800
	s_ashr_i32 s1, s0, 31
	s_lshl_b64 s[0:1], s[0:1], 2
	s_add_u32 s66, s28, s0
	s_addc_u32 s67, s29, s1
	s_add_u32 s72, s66, 0x1000
	s_addc_u32 s73, s67, 0
	s_add_i32 s0, s38, 0x1800
	v_lshl_add_u64 v[78:79], s[58:59], 0, v[200:201]
	s_ashr_i32 s0, s0, 13
	v_add_co_u32_e64 v78, s[4:5], s33, v78
	s_mulk_i32 s0, 0x1800
	s_nop 0
	v_addc_co_u32_e64 v79, vcc, 0, v79, s[4:5]
	s_ashr_i32 s1, s0, 31
	s_lshl_b64 s[0:1], s[0:1], 2
	s_add_u32 s52, s28, s0
	s_addc_u32 s53, s29, s1
	s_add_u32 s64, s52, 0x1000
	s_addc_u32 s65, s53, 0
	s_add_u32 s30, s30, 0x1000000
	s_addc_u32 s31, s31, 0
	s_add_u32 s36, s36, 0x2000000
	s_addc_u32 s37, s37, 0
	s_add_u32 s56, s56, 0x2000000
	s_addc_u32 s57, s57, 0
	s_add_u32 s58, s58, 0x1000000
	s_waitcnt vmcnt(17)
	v_pk_mul_f32 v[100:101], v[68:69], v[68:69]
	v_pk_mul_f32 v[102:103], v[66:67], v[66:67]
	s_waitcnt vmcnt(16)
	v_pk_mul_f32 v[104:105], v[60:61], v[60:61]
	v_pk_mul_f32 v[106:107], v[58:59], v[58:59]
	s_waitcnt vmcnt(13)
	v_pk_mul_f32 v[112:113], v[52:53], v[52:53]
	v_pk_mul_f32 v[114:115], v[50:51], v[50:51]
	s_waitcnt vmcnt(12)
	v_pk_mul_f32 v[116:117], v[44:45], v[44:45]
	v_pk_mul_f32 v[118:119], v[42:43], v[42:43]
	v_mul_f32_e32 v109, v56, v56
	v_mul_f32_e32 v108, v63, v63
	v_mul_f32_e32 v110, v65, v65
	s_waitcnt vmcnt(10)
	v_mul_f32_e32 v120, v47, v47
	v_mul_f32_e32 v122, v49, v49
	s_waitcnt vmcnt(9)
	v_pk_mul_f32 v[124:125], v[36:37], v[36:37]
	v_pk_mul_f32 v[126:127], v[34:35], v[34:35]
	s_waitcnt vmcnt(8)
	v_pk_mul_f32 v[128:129], v[32:33], v[32:33]
	v_pk_mul_f32 v[130:131], v[30:31], v[30:31]
	v_pk_mov_b32 v[140:141], v[102:103], v[100:101] op_sel:[1,0]
	v_mov_b32_e32 v103, v101
	v_pk_mov_b32 v[100:101], v[106:107], v[104:105] op_sel:[1,0]
	v_mov_b32_e32 v107, v105
	v_pk_mov_b32 v[104:105], v[114:115], v[112:113] op_sel:[1,0]
	v_mov_b32_e32 v115, v113
	v_pk_mov_b32 v[112:113], v[118:119], v[116:117] op_sel:[1,0]
	v_mov_b32_e32 v119, v117
	v_mul_f32_e32 v144, v57, v57
	v_mul_f32_e32 v147, v40, v40
	v_mul_f32_e32 v149, v41, v41
	s_waitcnt vmcnt(5)
	v_pk_mul_f32 v[132:133], v[20:21], v[20:21]
	v_pk_mul_f32 v[134:135], v[18:19], v[18:19]
	s_waitcnt vmcnt(4)
	v_pk_mul_f32 v[136:137], v[16:17], v[16:17]
	v_pk_mul_f32 v[138:139], v[14:15], v[14:15]
	v_pk_mov_b32 v[116:117], v[126:127], v[124:125] op_sel:[1,0]
	v_mov_b32_e32 v127, v125
	v_pk_mov_b32 v[124:125], v[130:131], v[128:129] op_sel:[1,0]
	v_mov_b32_e32 v131, v129
	v_pk_add_f32 v[102:103], v[140:141], v[102:103]
	v_pk_add_f32 v[100:101], v[100:101], v[106:107]
	v_pk_fma_f32 v[106:107], v[62:63], v[62:63], v[108:109] op_sel_hi:[1,1,0]
	v_pk_add_f32 v[112:113], v[112:113], v[118:119]
	v_pk_fma_f32 v[110:111], v[64:65], v[64:65], v[110:111] op_sel_hi:[1,1,0]
	v_pk_fma_f32 v[118:119], v[46:47], v[46:47], v[120:121] op_sel_hi:[1,1,0]
	v_pk_fma_f32 v[120:121], v[48:49], v[48:49], v[122:123] op_sel_hi:[1,1,0]
	v_mul_f32_e32 v142, v54, v54
	v_mul_f32_e32 v143, v55, v55
	v_pk_mov_b32 v[128:129], v[134:135], v[132:133] op_sel:[1,0]
	v_mov_b32_e32 v135, v133
	v_pk_mov_b32 v[132:133], v[138:139], v[136:137] op_sel:[1,0]
	v_mul_f32_e32 v136, v27, v27
	v_mul_f32_e32 v140, v29, v29
	s_waitcnt vmcnt(2)
	global_load_dwordx4 v[158:161], v[74:75], off
	global_load_dwordx4 v[174:177], v92, s[80:81]
	global_load_dwordx4 v[190:193], v92, s[78:79]
	global_load_dwordx4 v[162:165], v[74:75], off offset:1024
	global_load_dwordx4 v[178:181], v93, s[80:81]
	global_load_dwordx4 v[194:197], v92, s[78:79] offset:1024
	global_load_dwordx4 v[166:169], v[74:75], off offset:2048
	global_load_dwordx4 v[182:185], v94, s[80:81]
	global_load_dwordx4 v[206:209], v92, s[78:79] offset:2048
	global_load_dwordx4 v[170:173], v[74:75], off offset:3072
	global_load_dwordx4 v[186:189], v95, s[80:81]
	global_load_dwordx4 v[210:213], v92, s[78:79] offset:3072
	v_mul_f32_e32 v141, v2, v2
	v_mov_b32_e32 v107, v109
	v_pk_add_f32 v[104:105], v[104:105], v[114:115]
	v_mov_b32_e32 v111, v144
	v_mov_b32_e32 v119, v147
	v_mov_b32_e32 v121, v149
	v_pk_add_f32 v[116:117], v[116:117], v[126:127]
	v_pk_add_f32 v[124:125], v[124:125], v[130:131]
	v_pk_add_f32 v[102:103], v[102:103], v[102:103] op_sel:[0,1] op_sel_hi:[1,0]
	v_pk_add_f32 v[100:101], v[100:101], v[100:101] op_sel:[0,1] op_sel_hi:[1,0]
	v_mul_f32_e32 v145, v38, v38
	v_mul_f32_e32 v146, v39, v39
	v_mul_f32_e32 v150, v22, v22
	v_mul_f32_e32 v151, v23, v23
	v_mul_f32_e32 v152, v24, v24
	v_mul_f32_e32 v153, v25, v25
	v_mov_b32_e32 v139, v137
	v_pk_fma_f32 v[122:123], v[26:27], v[26:27], v[136:137] op_sel_hi:[1,1,0]
	v_pk_fma_f32 v[136:137], v[28:29], v[28:29], v[140:141] op_sel_hi:[1,1,0]
	v_pk_add_f32 v[106:107], v[106:107], v[110:111]
	v_pk_add_f32 v[104:105], v[104:105], v[104:105] op_sel:[0,1] op_sel_hi:[1,0]
	v_pk_add_f32 v[110:111], v[112:113], v[112:113] op_sel:[0,1] op_sel_hi:[1,0]
	v_pk_add_f32 v[112:113], v[118:119], v[120:121]
	v_pk_add_f32 v[116:117], v[116:117], v[116:117] op_sel:[0,1] op_sel_hi:[1,0]
	v_pk_add_f32 v[118:119], v[124:125], v[124:125] op_sel:[0,1] op_sel_hi:[1,0]
	v_mov_b32_e32 v103, v142
	v_mov_b32_e32 v101, v143
	v_mov_b32_e32 v123, v152
	v_mov_b32_e32 v137, v153
	v_mov_b32_e32 v105, v145
	v_mov_b32_e32 v111, v146
	v_mov_b32_e32 v117, v150
	v_mov_b32_e32 v119, v151
	v_pk_add_f32 v[100:101], v[102:103], v[100:101]
	v_mul_f32_e32 v108, v11, v11
	v_mul_f32_e32 v114, v13, v13
	v_pk_add_f32 v[126:127], v[128:129], v[134:135]
	v_pk_add_f32 v[128:129], v[132:133], v[138:139]
	v_pk_add_f32 v[120:121], v[122:123], v[136:137]
	v_pk_add_f32 v[102:103], v[104:105], v[110:111]
	v_pk_add_f32 v[104:105], v[116:117], v[118:119]
	v_pk_add_f32 v[100:101], v[100:101], v[106:107]
	v_mul_f32_e32 v154, v3, v3
	v_mul_f32_e32 v155, v4, v4
	v_mul_f32_e32 v156, v5, v5
	v_pk_fma_f32 v[108:109], v[10:11], v[10:11], v[108:109] op_sel_hi:[1,1,0]
	v_pk_fma_f32 v[114:115], v[12:13], v[12:13], v[114:115] op_sel_hi:[1,1,0]
	v_pk_add_f32 v[122:123], v[126:127], v[126:127] op_sel:[0,1] op_sel_hi:[1,0]
	v_pk_add_f32 v[124:125], v[128:129], v[128:129] op_sel:[0,1] op_sel_hi:[1,0]
	v_pk_add_f32 v[102:103], v[102:103], v[112:113]
	v_pk_add_f32 v[104:105], v[104:105], v[120:121]
	v_add_f32_e32 v100, v100, v101
	v_mov_b32_e32 v109, v155
	v_mov_b32_e32 v115, v156
	v_mov_b32_e32 v123, v141
	v_mov_b32_e32 v125, v154
	v_add_f32_e32 v101, v102, v103
	v_add_f32_e32 v102, v104, v105
	ds_bpermute_b32 v104, v84, v100
	v_pk_add_f32 v[108:109], v[108:109], v[114:115]
	v_pk_add_f32 v[110:111], v[122:123], v[124:125]
	ds_bpermute_b32 v105, v84, v101
	v_pk_add_f32 v[106:107], v[110:111], v[108:109]
	s_waitcnt lgkmcnt(1)
	v_add_f32_e32 v100, v100, v104
	v_add_f32_e32 v103, v106, v107
	ds_bpermute_b32 v106, v84, v102
	ds_bpermute_b32 v104, v85, v100
	s_waitcnt lgkmcnt(2)
	v_add_f32_e32 v101, v101, v105
	ds_bpermute_b32 v105, v85, v101
	ds_bpermute_b32 v107, v84, v103
	s_waitcnt lgkmcnt(3)
	v_add_f32_e32 v102, v102, v106
	ds_bpermute_b32 v106, v85, v102
	s_waitcnt lgkmcnt(3)
	v_add_f32_e32 v100, v100, v104
	ds_bpermute_b32 v104, v86, v100
	s_waitcnt lgkmcnt(3)
	v_add_f32_e32 v101, v101, v105
	ds_bpermute_b32 v105, v86, v101
	s_waitcnt lgkmcnt(2)
	v_add_f32_e32 v102, v102, v106
	ds_bpermute_b32 v106, v86, v102
	s_waitcnt lgkmcnt(2)
	v_add_f32_e32 v100, v100, v104
	ds_bpermute_b32 v104, v87, v100
	s_waitcnt lgkmcnt(2)
	v_add_f32_e32 v101, v101, v105
	ds_bpermute_b32 v105, v87, v101
	s_waitcnt lgkmcnt(2)
	v_add_f32_e32 v102, v102, v106
	ds_bpermute_b32 v106, v87, v102
	s_waitcnt lgkmcnt(2)
	v_add_f32_e32 v100, v100, v104
	ds_bpermute_b32 v104, v88, v100
	s_waitcnt lgkmcnt(2)
	v_add_f32_e32 v101, v101, v105
	ds_bpermute_b32 v105, v88, v101
	s_waitcnt lgkmcnt(2)
	v_add_f32_e32 v102, v102, v106
	ds_bpermute_b32 v106, v88, v102
	s_waitcnt lgkmcnt(2)
	v_add_f32_e32 v100, v100, v104
	ds_bpermute_b32 v104, v89, v100
	v_add_f32_e32 v103, v103, v107
	s_waitcnt lgkmcnt(2)
	v_add_f32_e32 v101, v101, v105
	ds_bpermute_b32 v107, v85, v103
	s_waitcnt lgkmcnt(2)
	v_add_f32_e32 v102, v102, v106
	ds_bpermute_b32 v105, v89, v101
	ds_bpermute_b32 v106, v89, v102
	s_waitcnt lgkmcnt(3)
	v_add_f32_e32 v100, v100, v104
	v_fmamk_f32 v100, v100, 0x3a800000, v90
	s_waitcnt lgkmcnt(2)
	v_add_f32_e32 v103, v103, v107
	s_waitcnt lgkmcnt(1)
	v_add_f32_e32 v101, v101, v105
	v_cmp_gt_f32_e32 vcc, s3, v100
	v_mul_f32_e32 v104, 0x4f800000, v100
	ds_bpermute_b32 v107, v86, v103
	s_waitcnt lgkmcnt(1)
	v_add_f32_e32 v102, v102, v106
	v_fmamk_f32 v101, v101, 0x3a800000, v90
	v_cndmask_b32_e32 v100, v100, v104, vcc
	v_fmamk_f32 v102, v102, 0x3a800000, v90
	v_cmp_gt_f32_e64 s[0:1], s3, v101
	v_mul_f32_e32 v105, 0x4f800000, v101
	v_sqrt_f32_e32 v104, v100
	v_cmp_gt_f32_e64 s[4:5], s3, v102
	v_mul_f32_e32 v106, 0x4f800000, v102
	v_cndmask_b32_e64 v101, v101, v105, s[0:1]
	v_cndmask_b32_e64 v102, v102, v106, s[4:5]
	v_sqrt_f32_e32 v105, v101
	v_sqrt_f32_e32 v106, v102
	s_waitcnt lgkmcnt(0)
	v_add_f32_e32 v103, v103, v107
	v_add_u32_e32 v107, -1, v104
	v_add_u32_e32 v108, 1, v104
	v_fma_f32 v113, -v107, v104, v100
	v_add_u32_e32 v109, -1, v105
	v_fma_f32 v114, -v108, v104, v100
	v_cmp_ge_f32_e64 s[12:13], 0, v113
	v_add_u32_e32 v110, 1, v105
	v_add_u32_e32 v111, -1, v106
	v_fma_f32 v115, -v109, v105, v101
	v_cmp_lt_f32_e64 s[16:17], 0, v114
	v_cndmask_b32_e64 v104, v104, v107, s[12:13]
	v_add_u32_e32 v112, 1, v106
	v_fma_f32 v116, -v110, v105, v101
	v_fma_f32 v117, -v111, v106, v102
	v_cmp_ge_f32_e64 s[18:19], 0, v115
	v_cndmask_b32_e64 v104, v104, v108, s[16:17]
	v_fma_f32 v118, -v112, v106, v102
	v_cmp_lt_f32_e64 s[20:21], 0, v116
	v_cmp_ge_f32_e64 s[22:23], 0, v117
	v_cndmask_b32_e64 v105, v105, v109, s[18:19]
	v_mul_f32_e32 v107, 0x37800000, v104
	v_cmp_class_f32_e64 s[6:7], v100, v91
	v_cmp_lt_f32_e64 s[24:25], 0, v118
	v_cndmask_b32_e64 v106, v106, v111, s[22:23]
	v_cndmask_b32_e64 v105, v105, v110, s[20:21]
	v_cndmask_b32_e32 v104, v104, v107, vcc
	v_cndmask_b32_e64 v106, v106, v112, s[24:25]
	v_mul_f32_e32 v108, 0x37800000, v105
	v_cndmask_b32_e64 v100, v104, v100, s[6:7]
	v_cmp_class_f32_e64 s[8:9], v101, v91
	v_mul_f32_e32 v109, 0x37800000, v106
	v_cndmask_b32_e64 v105, v105, v108, s[0:1]
	v_div_scale_f32 v104, s[0:1], v100, v100, 1.0
	v_cmp_class_f32_e64 s[10:11], v102, v91
	v_cndmask_b32_e64 v106, v106, v109, s[4:5]
	v_cndmask_b32_e64 v101, v105, v101, s[8:9]
	v_rcp_f32_e32 v110, v104
	v_cndmask_b32_e64 v102, v106, v102, s[10:11]
	v_div_scale_f32 v106, s[0:1], v101, v101, 1.0
	v_div_scale_f32 v108, s[4:5], v102, v102, 1.0
	v_rcp_f32_e32 v111, v106
	v_rcp_f32_e32 v112, v108
	v_fma_f32 v113, -v104, v110, 1.0
	v_div_scale_f32 v105, vcc, 1.0, v100, 1.0
	v_fmac_f32_e32 v110, v113, v110
	v_fma_f32 v114, -v106, v111, 1.0
	v_mul_f32_e32 v113, v105, v110
	v_div_scale_f32 v107, s[0:1], 1.0, v101, 1.0
	v_fma_f32 v115, -v108, v112, 1.0
	v_fmac_f32_e32 v111, v114, v111
	v_fma_f32 v116, -v104, v113, v105
	v_div_scale_f32 v109, s[4:5], 1.0, v102, 1.0
	v_fmac_f32_e32 v112, v115, v112
	v_mul_f32_e32 v114, v107, v111
	v_fmac_f32_e32 v113, v116, v110
	v_mul_f32_e32 v115, v109, v112
	v_fma_f32 v117, -v106, v114, v107
	v_fma_f32 v104, -v104, v113, v105
	v_fma_f32 v118, -v108, v115, v109
	v_fmac_f32_e32 v114, v117, v111
	v_div_fmas_f32 v104, v104, v110, v113
	v_fmac_f32_e32 v115, v118, v112
	v_fma_f32 v105, -v106, v114, v107
	v_div_fixup_f32 v100, v104, v100, 1.0
	s_mov_b64 vcc, s[0:1]
	v_fma_f32 v106, -v108, v115, v109
	v_div_fmas_f32 v104, v105, v111, v114
	v_pk_mul_f32 v[68:69], v[68:69], v[100:101] op_sel_hi:[1,0]
	v_pk_mul_f32 v[66:67], v[66:67], v[100:101] op_sel_hi:[1,0]
	s_mov_b64 vcc, s[4:5]
	s_waitcnt vmcnt(0)
	v_pk_add_f32 v[98:99], v[98:99], 1.0 op_sel_hi:[1,0]
	v_pk_add_f32 v[96:97], v[96:97], 1.0 op_sel_hi:[1,0]
	v_pk_mul_f32 v[60:61], v[60:61], v[100:101] op_sel_hi:[1,0]
	v_pk_mul_f32 v[58:59], v[58:59], v[100:101] op_sel_hi:[1,0]
	v_pk_mul_f32 v[64:65], v[64:65], v[100:101] op_sel_hi:[1,0]
	v_pk_mul_f32 v[62:63], v[62:63], v[100:101] op_sel_hi:[1,0]
	v_pk_mul_f32 v[56:57], v[56:57], v[100:101] op_sel_hi:[1,0]
	v_pk_mul_f32 v[54:55], v[54:55], v[100:101] op_sel_hi:[1,0]
	v_div_fixup_f32 v100, v104, v101, 1.0
	v_div_fmas_f32 v104, v106, v112, v115
	v_pk_mul_f32 v[66:67], v[6:7], v[66:67]
	v_pk_mul_f32 v[8:9], v[8:9], v[68:69]
	v_pk_mul_f32 v[52:53], v[52:53], v[100:101] op_sel_hi:[1,0]
	v_pk_mul_f32 v[50:51], v[50:51], v[100:101] op_sel_hi:[1,0]
	v_pk_mul_f32 v[44:45], v[44:45], v[100:101] op_sel_hi:[1,0]
	v_pk_mul_f32 v[42:43], v[42:43], v[100:101] op_sel_hi:[1,0]
	v_pk_mul_f32 v[48:49], v[48:49], v[100:101] op_sel_hi:[1,0]
	v_pk_mul_f32 v[46:47], v[46:47], v[100:101] op_sel_hi:[1,0]
	v_pk_mul_f32 v[68:69], v[40:41], v[100:101] op_sel_hi:[1,0]
	v_pk_mul_f32 v[100:101], v[38:39], v[100:101] op_sel_hi:[1,0]
	v_div_fixup_f32 v6, v104, v102, 1.0
	v_pk_fma_f32 v[8:9], v[98:99], v[8:9], v[72:73]
	v_pk_fma_f32 v[38:39], v[96:97], v[66:67], v[70:71]
	v_pk_mul_f32 v[66:67], v[36:37], v[6:7] op_sel_hi:[1,0]
	v_pk_mul_f32 v[70:71], v[34:35], v[6:7] op_sel_hi:[1,0]
	v_pk_mul_f32 v[72:73], v[32:33], v[6:7] op_sel_hi:[1,0]
	v_pk_mul_f32 v[96:97], v[30:31], v[6:7] op_sel_hi:[1,0]
	v_bfe_u32 v7, v38, 16, 1
	v_bfe_u32 v31, v8, 16, 1
	v_bfe_u32 v30, v39, 16, 1
	v_bfe_u32 v32, v9, 16, 1
	v_add3_u32 v7, v38, v7, s26
	v_add3_u32 v8, v8, v31, s26
	v_add3_u32 v30, v39, v30, s26
	v_add3_u32 v9, v9, v32, s26
	v_lshrrev_b32_e32 v7, 16, v7
	v_lshrrev_b32_e32 v31, 16, v8
	v_and_or_b32 v8, v30, s27, v7
	v_and_or_b32 v9, v9, s27, v31
	global_store_dwordx2 v[82:83], v[8:9], off
	s_addc_u32 s59, s59, 0
	s_add_u32 s60, s60, 0x1000000
	s_addc_u32 s61, s61, 0
	s_add_u32 s62, s62, 0x2000000
	s_addc_u32 s63, s63, 0
	s_add_u32 s68, s68, 0x1000000
	s_addc_u32 s69, s69, 0
	s_add_u32 s70, s70, 0x2000000
	s_addc_u32 s71, s71, 0
	s_cmpk_lt_i32 s38, 0x2000
	s_cbranch_scc0 .Lp0b_nowarm
	v_lshl_add_u64 v[252:253], s[36:37], 0, v[204:205]
	global_load_dword v254, v[252:253], off
	global_load_dword v254, v[252:253], off offset:1024
	global_load_dword v254, v[252:253], off offset:2048
	global_load_dword v254, v[252:253], off offset:3072
	v_lshl_add_u64 v[252:253], s[70:71], 0, v[204:205]
	global_load_dword v254, v[252:253], off
	global_load_dword v254, v[252:253], off offset:1024
	global_load_dword v254, v[252:253], off offset:2048
	global_load_dword v254, v[252:253], off offset:3072
	v_lshl_add_u64 v[252:253], s[62:63], 0, v[204:205]
	global_load_dword v254, v[252:253], off
	global_load_dword v254, v[252:253], off offset:1024
	global_load_dword v254, v[252:253], off offset:2048
	global_load_dword v254, v[252:253], off offset:3072
	v_lshl_add_u64 v[252:253], s[56:57], 0, v[204:205]
	global_load_dword v254, v[252:253], off
	global_load_dword v254, v[252:253], off offset:1024
	global_load_dword v254, v[252:253], off offset:2048
	global_load_dword v254, v[252:253], off offset:3072
.Lp0b_nowarm:
	v_pk_mul_f32 v[8:9], v[162:163], v[58:59]
	v_pk_mul_f32 v[30:31], v[164:165], v[60:61]
	v_pk_add_f32 v[32:33], v[180:181], 1.0 op_sel_hi:[1,0]
	v_pk_add_f32 v[34:35], v[178:179], 1.0 op_sel_hi:[1,0]
	v_pk_fma_f32 v[30:31], v[32:33], v[30:31], v[196:197]
	v_pk_fma_f32 v[8:9], v[34:35], v[8:9], v[194:195]
	v_bfe_u32 v33, v30, 16, 1
	v_bfe_u32 v7, v8, 16, 1
	v_bfe_u32 v32, v9, 16, 1
	v_bfe_u32 v34, v31, 16, 1
	v_add3_u32 v7, v8, v7, s26
	v_add3_u32 v8, v9, v32, s26
	v_add3_u32 v9, v30, v33, s26
	v_add3_u32 v30, v31, v34, s26
	v_lshrrev_b32_e32 v7, 16, v7
	v_lshrrev_b32_e32 v9, 16, v9
	v_and_or_b32 v8, v8, s27, v7
	v_and_or_b32 v9, v30, s27, v9
	global_store_dwordx2 v[82:83], v[8:9], off offset:512
	v_pk_mul_f32 v[8:9], v[166:167], v[62:63]
	v_pk_mul_f32 v[30:31], v[168:169], v[64:65]
	v_pk_add_f32 v[32:33], v[184:185], 1.0 op_sel_hi:[1,0]
	v_pk_add_f32 v[34:35], v[182:183], 1.0 op_sel_hi:[1,0]
	v_pk_fma_f32 v[30:31], v[30:31], v[32:33], v[208:209]
	v_pk_fma_f32 v[8:9], v[8:9], v[34:35], v[206:207]
	v_bfe_u32 v33, v30, 16, 1
	v_bfe_u32 v7, v8, 16, 1
	v_bfe_u32 v32, v9, 16, 1
	v_bfe_u32 v34, v31, 16, 1
	v_add3_u32 v7, v8, v7, s26
	v_add3_u32 v8, v9, v32, s26
	v_add3_u32 v9, v30, v33, s26
	v_add3_u32 v30, v31, v34, s26
	v_lshrrev_b32_e32 v7, 16, v7
	v_lshrrev_b32_e32 v9, 16, v9
	v_and_or_b32 v8, v8, s27, v7
	v_and_or_b32 v9, v30, s27, v9
	global_store_dwordx2 v[82:83], v[8:9], off offset:1024
	v_pk_mul_f32 v[8:9], v[54:55], v[170:171]
	v_pk_mul_f32 v[30:31], v[56:57], v[172:173]
	v_pk_add_f32 v[32:33], v[188:189], 1.0 op_sel_hi:[1,0]
	v_pk_add_f32 v[34:35], v[186:187], 1.0 op_sel_hi:[1,0]
	v_pk_fma_f32 v[30:31], v[30:31], v[32:33], v[212:213]
	v_pk_fma_f32 v[8:9], v[8:9], v[34:35], v[210:211]
	v_bfe_u32 v33, v30, 16, 1
	v_bfe_u32 v7, v8, 16, 1
	v_bfe_u32 v32, v9, 16, 1
	v_bfe_u32 v34, v31, 16, 1
	v_add3_u32 v7, v8, v7, s26
	v_add3_u32 v8, v9, v32, s26
	v_add3_u32 v9, v30, v33, s26
	v_add3_u32 v30, v31, v34, s26
	v_lshrrev_b32_e32 v7, 16, v7
	v_lshrrev_b32_e32 v9, 16, v9
	v_and_or_b32 v8, v8, s27, v7
	v_and_or_b32 v9, v30, s27, v9
	global_store_dwordx2 v[82:83], v[8:9], off offset:1536
	v_pk_mul_f32 v[8:9], v[158:159], v[50:51]
	v_pk_mul_f32 v[30:31], v[160:161], v[52:53]
	v_pk_add_f32 v[32:33], v[176:177], 1.0 op_sel_hi:[1,0]
	v_pk_add_f32 v[34:35], v[174:175], 1.0 op_sel_hi:[1,0]
	v_pk_fma_f32 v[30:31], v[32:33], v[30:31], v[192:193]
	v_pk_fma_f32 v[8:9], v[34:35], v[8:9], v[190:191]
	v_bfe_u32 v33, v30, 16, 1
	v_bfe_u32 v7, v8, 16, 1
	v_bfe_u32 v32, v9, 16, 1
	v_bfe_u32 v34, v31, 16, 1
	v_add3_u32 v7, v8, v7, s26
	v_add3_u32 v8, v9, v32, s26
	v_add3_u32 v9, v30, v33, s26
	v_add3_u32 v30, v31, v34, s26
	v_lshrrev_b32_e32 v7, 16, v7
	v_lshrrev_b32_e32 v9, 16, v9
	v_and_or_b32 v8, v8, s27, v7
	v_and_or_b32 v9, v30, s27, v9
	global_store_dwordx2 v[80:81], v[8:9], off
	v_pk_mul_f32 v[8:9], v[162:163], v[42:43]
	v_pk_mul_f32 v[30:31], v[164:165], v[44:45]
	v_pk_add_f32 v[32:33], v[180:181], 1.0 op_sel_hi:[1,0]
	v_pk_add_f32 v[34:35], v[178:179], 1.0 op_sel_hi:[1,0]
	v_pk_fma_f32 v[30:31], v[32:33], v[30:31], v[196:197]
	v_pk_fma_f32 v[8:9], v[34:35], v[8:9], v[194:195]
	v_bfe_u32 v33, v30, 16, 1
	v_bfe_u32 v7, v8, 16, 1
	v_bfe_u32 v32, v9, 16, 1
	v_bfe_u32 v34, v31, 16, 1
	v_add3_u32 v7, v8, v7, s26
	v_add3_u32 v8, v9, v32, s26
	v_add3_u32 v9, v30, v33, s26
	v_add3_u32 v30, v31, v34, s26
	v_lshrrev_b32_e32 v7, 16, v7
	v_lshrrev_b32_e32 v9, 16, v9
	v_and_or_b32 v8, v8, s27, v7
	v_and_or_b32 v9, v30, s27, v9
	global_store_dwordx2 v[80:81], v[8:9], off offset:512
	v_pk_mul_f32 v[8:9], v[166:167], v[46:47]
	v_pk_mul_f32 v[30:31], v[168:169], v[48:49]
	v_pk_add_f32 v[32:33], v[184:185], 1.0 op_sel_hi:[1,0]
	v_pk_add_f32 v[34:35], v[182:183], 1.0 op_sel_hi:[1,0]
	v_pk_fma_f32 v[30:31], v[30:31], v[32:33], v[208:209]
	v_pk_fma_f32 v[8:9], v[8:9], v[34:35], v[206:207]
	v_bfe_u32 v33, v30, 16, 1
	v_bfe_u32 v7, v8, 16, 1
	v_bfe_u32 v32, v9, 16, 1
	v_bfe_u32 v34, v31, 16, 1
	v_add3_u32 v7, v8, v7, s26
	v_add3_u32 v8, v9, v32, s26
	v_add3_u32 v9, v30, v33, s26
	v_add3_u32 v30, v31, v34, s26
	v_lshrrev_b32_e32 v7, 16, v7
	v_lshrrev_b32_e32 v9, 16, v9
	v_and_or_b32 v8, v8, s27, v7
	v_and_or_b32 v9, v30, s27, v9
	global_store_dwordx2 v[80:81], v[8:9], off offset:1024
	v_pk_mul_f32 v[8:9], v[100:101], v[170:171]
	v_pk_mul_f32 v[30:31], v[68:69], v[172:173]
	v_pk_add_f32 v[32:33], v[188:189], 1.0 op_sel_hi:[1,0]
	v_pk_add_f32 v[34:35], v[186:187], 1.0 op_sel_hi:[1,0]
	v_pk_fma_f32 v[30:31], v[30:31], v[32:33], v[212:213]
	v_pk_fma_f32 v[8:9], v[8:9], v[34:35], v[210:211]
	v_bfe_u32 v33, v30, 16, 1
	v_bfe_u32 v7, v8, 16, 1
	v_bfe_u32 v32, v9, 16, 1
	v_bfe_u32 v34, v31, 16, 1
	v_add3_u32 v7, v8, v7, s26
	v_add3_u32 v8, v9, v32, s26
	v_add3_u32 v9, v30, v33, s26
	v_add3_u32 v30, v31, v34, s26
	v_lshrrev_b32_e32 v7, 16, v7
	v_lshrrev_b32_e32 v9, 16, v9
	v_and_or_b32 v8, v8, s27, v7
	v_and_or_b32 v9, v30, s27, v9
	global_store_dwordx2 v[80:81], v[8:9], off offset:1536
	v_pk_mul_f32 v[8:9], v[158:159], v[70:71]
	v_pk_mul_f32 v[30:31], v[160:161], v[66:67]
	v_pk_add_f32 v[32:33], v[176:177], 1.0 op_sel_hi:[1,0]
	v_pk_add_f32 v[34:35], v[174:175], 1.0 op_sel_hi:[1,0]
	v_pk_fma_f32 v[30:31], v[32:33], v[30:31], v[192:193]
	v_pk_fma_f32 v[8:9], v[34:35], v[8:9], v[190:191]
	v_bfe_u32 v33, v30, 16, 1
	v_bfe_u32 v7, v8, 16, 1
	v_bfe_u32 v32, v9, 16, 1
	v_bfe_u32 v34, v31, 16, 1
	v_add3_u32 v7, v8, v7, s26
	v_add3_u32 v8, v9, v32, s26
	v_add3_u32 v9, v30, v33, s26
	v_add3_u32 v30, v31, v34, s26
	v_lshrrev_b32_e32 v7, 16, v7
	v_lshrrev_b32_e32 v9, 16, v9
	v_and_or_b32 v8, v8, s27, v7
	v_and_or_b32 v9, v30, s27, v9
	global_store_dwordx2 v[78:79], v[8:9], off
	v_pk_mul_f32 v[8:9], v[162:163], v[96:97]
	v_pk_mul_f32 v[30:31], v[164:165], v[72:73]
	v_pk_add_f32 v[32:33], v[180:181], 1.0 op_sel_hi:[1,0]
	v_pk_add_f32 v[34:35], v[178:179], 1.0 op_sel_hi:[1,0]
	v_pk_fma_f32 v[30:31], v[32:33], v[30:31], v[196:197]
	v_pk_fma_f32 v[8:9], v[34:35], v[8:9], v[194:195]
	v_bfe_u32 v33, v30, 16, 1
	v_bfe_u32 v7, v8, 16, 1
	v_bfe_u32 v32, v9, 16, 1
	v_bfe_u32 v34, v31, 16, 1
	v_add3_u32 v7, v8, v7, s26
	v_add3_u32 v8, v9, v32, s26
	v_add3_u32 v9, v30, v33, s26
	v_add3_u32 v30, v31, v34, s26
	v_lshrrev_b32_e32 v7, 16, v7
	v_lshrrev_b32_e32 v9, 16, v9
	v_and_or_b32 v8, v8, s27, v7
	v_and_or_b32 v9, v30, s27, v9
	global_store_dwordx2 v[78:79], v[8:9], off offset:512
	ds_bpermute_b32 v7, v87, v103
	s_waitcnt lgkmcnt(0)
	v_add_f32_e32 v7, v103, v7
	v_pk_mul_f32 v[8:9], v[28:29], v[6:7] op_sel_hi:[1,0]
	v_pk_mul_f32 v[26:27], v[26:27], v[6:7] op_sel_hi:[1,0]
	v_pk_mul_f32 v[8:9], v[168:169], v[8:9]
	v_pk_mul_f32 v[26:27], v[166:167], v[26:27]
	v_pk_add_f32 v[28:29], v[184:185], 1.0 op_sel_hi:[1,0]
	v_pk_add_f32 v[30:31], v[182:183], 1.0 op_sel_hi:[1,0]
	v_pk_fma_f32 v[8:9], v[8:9], v[28:29], v[208:209]
	v_pk_fma_f32 v[26:27], v[26:27], v[30:31], v[206:207]
	v_bfe_u32 v30, v8, 16, 1
	v_bfe_u32 v28, v26, 16, 1
	v_bfe_u32 v29, v27, 16, 1
	v_bfe_u32 v31, v9, 16, 1
	v_add3_u32 v26, v26, v28, s26
	v_add3_u32 v8, v8, v30, s26
	v_add3_u32 v27, v27, v29, s26
	v_add3_u32 v9, v9, v31, s26
	v_lshrrev_b32_e32 v26, 16, v26
	v_lshrrev_b32_e32 v28, 16, v8
	v_and_or_b32 v8, v27, s27, v26
	v_and_or_b32 v9, v9, s27, v28
	global_store_dwordx2 v[78:79], v[8:9], off offset:1024
	ds_bpermute_b32 v8, v88, v7
	s_waitcnt lgkmcnt(0)
	v_add_f32_e32 v7, v7, v8
	ds_bpermute_b32 v8, v89, v7
	s_waitcnt lgkmcnt(0)
	v_add_f32_e32 v7, v7, v8
	v_fmamk_f32 v7, v7, 0x3a800000, v90
	v_cmp_gt_f32_e32 vcc, s3, v7
	v_mul_f32_e32 v8, 0x4f800000, v7
	s_nop 0
	v_cndmask_b32_e32 v38, v7, v8, vcc
	v_pk_mul_f32 v[8:9], v[24:25], v[6:7] op_sel_hi:[1,0]
	v_pk_mul_f32 v[6:7], v[22:23], v[6:7] op_sel_hi:[1,0]
	v_sqrt_f32_e32 v39, v38
	v_cmp_class_f32_e64 s[0:1], v38, v91
	v_pk_mul_f32 v[6:7], v[6:7], v[170:171]
	v_pk_mul_f32 v[8:9], v[8:9], v[172:173]
	v_pk_add_f32 v[22:23], v[188:189], 1.0 op_sel_hi:[1,0]
	v_pk_add_f32 v[24:25], v[186:187], 1.0 op_sel_hi:[1,0]
	v_pk_fma_f32 v[8:9], v[8:9], v[22:23], v[212:213]
	v_pk_fma_f32 v[6:7], v[6:7], v[24:25], v[210:211]
	v_bfe_u32 v24, v8, 16, 1
	v_bfe_u32 v22, v6, 16, 1
	v_bfe_u32 v23, v7, 16, 1
	v_bfe_u32 v25, v9, 16, 1
	v_add3_u32 v6, v6, v22, s26
	v_add3_u32 v8, v8, v24, s26
	v_add3_u32 v7, v7, v23, s26
	v_add3_u32 v9, v9, v25, s26
	v_lshrrev_b32_e32 v6, 16, v6
	v_lshrrev_b32_e32 v8, 16, v8
	v_and_or_b32 v6, v7, s27, v6
	v_and_or_b32 v7, v9, s27, v8
	global_store_dwordx2 v[78:79], v[6:7], off offset:1536
	v_add_u32_e32 v6, -1, v39
	v_add_u32_e32 v7, 1, v39
	v_fma_f32 v8, -v6, v39, v38
	v_fma_f32 v9, -v7, v39, v38
	v_cmp_ge_f32_e64 s[4:5], 0, v8
	v_cmp_lt_f32_e64 s[6:7], 0, v9
	s_nop 0
	v_cndmask_b32_e64 v6, v39, v6, s[4:5]
	v_cndmask_b32_e64 v6, v6, v7, s[6:7]
	v_mul_f32_e32 v7, 0x37800000, v6
	v_cndmask_b32_e32 v6, v6, v7, vcc
	v_cndmask_b32_e64 v6, v6, v38, s[0:1]
	v_div_scale_f32 v7, s[0:1], v6, v6, 1.0
	v_rcp_f32_e32 v9, v7
	v_div_scale_f32 v8, vcc, 1.0, v6, 1.0
	s_add_i32 s0, s38, 0x2000
	v_fma_f32 v34, -v7, v9, 1.0
	v_fmac_f32_e32 v9, v34, v9
	v_mul_f32_e32 v34, v8, v9
	v_fma_f32 v35, -v7, v34, v8
	v_fmac_f32_e32 v34, v35, v9
	v_fma_f32 v7, -v7, v34, v8
	v_div_fmas_f32 v7, v7, v9, v34
	v_div_fixup_f32 v6, v7, v6, 1.0
	v_pk_mul_f32 v[8:9], v[20:21], v[6:7] op_sel_hi:[1,0]
	v_pk_mul_f32 v[18:19], v[18:19], v[6:7] op_sel_hi:[1,0]
	s_cmpk_lt_i32 s38, 0x2000
	s_mov_b32 s38, s0
	v_pk_mul_f32 v[18:19], v[158:159], v[18:19]
	v_pk_mul_f32 v[8:9], v[160:161], v[8:9]
	v_pk_add_f32 v[20:21], v[176:177], 1.0 op_sel_hi:[1,0]
	v_pk_add_f32 v[22:23], v[174:175], 1.0 op_sel_hi:[1,0]
	v_pk_fma_f32 v[8:9], v[20:21], v[8:9], v[192:193]
	v_pk_fma_f32 v[18:19], v[22:23], v[18:19], v[190:191]
	v_bfe_u32 v21, v8, 16, 1
	v_bfe_u32 v7, v18, 16, 1
	v_bfe_u32 v20, v19, 16, 1
	v_bfe_u32 v22, v9, 16, 1
	v_add3_u32 v7, v18, v7, s26
	v_add3_u32 v8, v8, v21, s26
	v_add3_u32 v18, v19, v20, s26
	v_add3_u32 v9, v9, v22, s26
	v_lshrrev_b32_e32 v7, 16, v7
	v_lshrrev_b32_e32 v19, 16, v8
	v_and_or_b32 v8, v18, s27, v7
	v_and_or_b32 v9, v9, s27, v19
	global_store_dwordx2 v[76:77], v[8:9], off
	v_pk_mul_f32 v[8:9], v[16:17], v[6:7] op_sel_hi:[1,0]
	v_pk_mul_f32 v[14:15], v[14:15], v[6:7] op_sel_hi:[1,0]
	v_pk_mul_f32 v[8:9], v[164:165], v[8:9]
	v_pk_mul_f32 v[14:15], v[162:163], v[14:15]
	v_pk_add_f32 v[16:17], v[180:181], 1.0 op_sel_hi:[1,0]
	v_pk_add_f32 v[18:19], v[178:179], 1.0 op_sel_hi:[1,0]
	v_pk_fma_f32 v[8:9], v[16:17], v[8:9], v[196:197]
	v_pk_fma_f32 v[14:15], v[18:19], v[14:15], v[194:195]
	v_bfe_u32 v17, v8, 16, 1
	v_bfe_u32 v7, v14, 16, 1
	v_bfe_u32 v16, v15, 16, 1
	v_bfe_u32 v18, v9, 16, 1
	v_add3_u32 v7, v14, v7, s26
	v_add3_u32 v8, v8, v17, s26
	v_add3_u32 v14, v15, v16, s26
	v_add3_u32 v9, v9, v18, s26
	v_lshrrev_b32_e32 v7, 16, v7
	v_lshrrev_b32_e32 v15, 16, v8
	v_and_or_b32 v8, v14, s27, v7
	v_and_or_b32 v9, v9, s27, v15
	global_store_dwordx2 v[76:77], v[8:9], off offset:512
	v_pk_mul_f32 v[8:9], v[12:13], v[6:7] op_sel_hi:[1,0]
	v_pk_mul_f32 v[10:11], v[10:11], v[6:7] op_sel_hi:[1,0]
	v_pk_mul_f32 v[8:9], v[168:169], v[8:9]
	v_pk_mul_f32 v[10:11], v[166:167], v[10:11]
	v_pk_add_f32 v[12:13], v[184:185], 1.0 op_sel_hi:[1,0]
	v_pk_add_f32 v[14:15], v[182:183], 1.0 op_sel_hi:[1,0]
	v_pk_fma_f32 v[8:9], v[8:9], v[12:13], v[208:209]
	v_pk_fma_f32 v[10:11], v[10:11], v[14:15], v[206:207]
	v_bfe_u32 v13, v8, 16, 1
	v_bfe_u32 v7, v10, 16, 1
	v_bfe_u32 v12, v11, 16, 1
	v_bfe_u32 v14, v9, 16, 1
	v_add3_u32 v7, v10, v7, s26
	v_add3_u32 v8, v8, v13, s26
	v_add3_u32 v10, v11, v12, s26
	v_add3_u32 v9, v9, v14, s26
	v_lshrrev_b32_e32 v7, 16, v7
	v_lshrrev_b32_e32 v11, 16, v8
	v_and_or_b32 v8, v10, s27, v7
	v_and_or_b32 v9, v9, s27, v11
	global_store_dwordx2 v[76:77], v[8:9], off offset:1024
	s_nop 0
	v_pk_mul_f32 v[4:5], v[4:5], v[6:7] op_sel_hi:[1,0]
	v_pk_mul_f32 v[2:3], v[2:3], v[6:7] op_sel_hi:[1,0]
	v_pk_mul_f32 v[4:5], v[4:5], v[172:173]
	v_pk_mul_f32 v[2:3], v[2:3], v[170:171]
	v_pk_add_f32 v[6:7], v[188:189], 1.0 op_sel_hi:[1,0]
	v_pk_add_f32 v[8:9], v[186:187], 1.0 op_sel_hi:[1,0]
	v_pk_fma_f32 v[4:5], v[4:5], v[6:7], v[212:213]
	v_pk_fma_f32 v[2:3], v[2:3], v[8:9], v[210:211]
	v_bfe_u32 v8, v4, 16, 1
	v_bfe_u32 v6, v2, 16, 1
	v_bfe_u32 v7, v3, 16, 1
	v_bfe_u32 v9, v5, 16, 1
	v_add3_u32 v2, v2, v6, s26
	v_add3_u32 v4, v4, v8, s26
	v_add3_u32 v3, v3, v7, s26
	v_add3_u32 v5, v5, v9, s26
	v_lshrrev_b32_e32 v2, 16, v2
	v_lshrrev_b32_e32 v4, 16, v4
	v_and_or_b32 v2, v3, s27, v2
	v_and_or_b32 v3, v5, s27, v4
	global_store_dwordx2 v[76:77], v[2:3], off offset:1536
	s_cbranch_scc1 .LBB0_138
	v_readlane_b32 s16, v251, 9
	v_readlane_b32 s17, v251, 10
	v_readlane_b32 s18, v251, 11
	v_readlane_b32 s19, v251, 12
	v_readlane_b32 s20, v251, 13
	v_readlane_b32 s21, v251, 14
	v_readlane_b32 s22, v251, 15
	v_readlane_b32 s23, v251, 16
	v_readlane_b32 s24, v251, 17
	v_readlane_b32 s25, v251, 18
	v_readlane_b32 s26, v251, 19
	v_readlane_b32 s27, v251, 20
	v_readlane_b32 s28, v251, 21
	v_readlane_b32 s29, v251, 22
	v_readlane_b32 s30, v251, 23
	v_readlane_b32 s31, v251, 24
	v_readlane_b32 s16, v251, 25
	v_readlane_b32 s17, v251, 26
	v_readlane_b32 s18, v251, 27
	v_readlane_b32 s19, v251, 28
	v_readlane_b32 s20, v251, 29
	v_readlane_b32 s21, v251, 30
	v_readlane_b32 s22, v251, 31
	v_readlane_b32 s23, v251, 32
	v_readlane_b32 s24, v251, 33
	v_readlane_b32 s25, v251, 34
	v_readlane_b32 s26, v251, 35
	v_readlane_b32 s27, v251, 36
	v_readlane_b32 s28, v251, 37
	v_readlane_b32 s29, v251, 38
	v_readlane_b32 s30, v251, 39
	v_readlane_b32 s31, v251, 40
